# L2 prefetch of pool staging rows and decode K/V rows (LDS-DMA to unused LDS corner) issued inside the attention unit's compute stretch
# speedup vs baseline: 1.0079x; 1.0079x over previous
.LBB0_282:
	s_or_b64 exec, exec, s[4:5]
	v_and_b32_e32 v49, 0xffff0000, v14
	v_lshlrev_b32_e32 v48, 16, v14
	v_lshlrev_b32_e32 v39, 16, v6
	v_and_b32_e32 v38, 0xffff0000, v6
	v_lshlrev_b32_e32 v37, 16, v7
	v_and_b32_e32 v36, 0xffff0000, v7
	v_lshlrev_b32_e32 v7, 16, v9
	v_and_b32_e32 v6, 0xffff0000, v9
	v_mul_f32_e32 v9, v49, v49
	v_lshlrev_b32_e32 v54, 16, v15
	v_fmac_f32_e32 v9, v48, v48
	v_and_b32_e32 v55, 0xffff0000, v15
	v_fmac_f32_e32 v9, v54, v54
	v_lshlrev_b32_e32 v56, 16, v16
	v_fmac_f32_e32 v9, v55, v55
	v_and_b32_e32 v57, 0xffff0000, v16
	v_fmac_f32_e32 v9, v56, v56
	v_lshlrev_b32_e32 v58, 16, v17
	v_fmac_f32_e32 v9, v57, v57
	v_and_b32_e32 v59, 0xffff0000, v17
	v_fmac_f32_e32 v9, v58, v58
	v_lshlrev_b32_e32 v47, 16, v10
	v_fmac_f32_e32 v9, v59, v59
	v_and_b32_e32 v46, 0xffff0000, v10
	v_fmac_f32_e32 v9, v47, v47
	v_lshlrev_b32_e32 v45, 16, v11
	v_fmac_f32_e32 v9, v46, v46
	v_and_b32_e32 v44, 0xffff0000, v11
	v_fmac_f32_e32 v9, v45, v45
	v_lshlrev_b32_e32 v43, 16, v12
	v_fmac_f32_e32 v9, v44, v44
	v_and_b32_e32 v42, 0xffff0000, v12
	v_fmac_f32_e32 v9, v43, v43
	v_lshlrev_b32_e32 v41, 16, v13
	v_fmac_f32_e32 v9, v42, v42
	v_and_b32_e32 v40, 0xffff0000, v13
	v_fmac_f32_e32 v9, v41, v41
	v_fmac_f32_e32 v9, v40, v40
	v_fmac_f32_e32 v9, v39, v39
	v_fmac_f32_e32 v9, v38, v38
	v_fmac_f32_e32 v9, v37, v37
	v_lshlrev_b32_e32 v35, 16, v8
	v_fmac_f32_e32 v9, v36, v36
	v_and_b32_e32 v8, 0xffff0000, v8
	v_fmac_f32_e32 v9, v35, v35
	v_fmac_f32_e32 v9, v8, v8
	v_fmac_f32_e32 v9, v7, v7
	v_lshlrev_b32_e32 v17, 16, v2
	v_fmac_f32_e32 v9, v6, v6
	v_and_b32_e32 v16, 0xffff0000, v2
	v_fmac_f32_e32 v9, v17, v17
	v_lshlrev_b32_e32 v15, 16, v3
	v_fmac_f32_e32 v9, v16, v16
	v_and_b32_e32 v14, 0xffff0000, v3
	v_fmac_f32_e32 v9, v15, v15
	v_and_b32_e32 v12, 0xffff0000, v4
	v_lshlrev_b32_e32 v13, 16, v4
	v_fmac_f32_e32 v9, v14, v14
	v_pk_mul_f32 v[2:3], v[12:13], v[12:13]
	v_and_b32_e32 v10, 0xffff0000, v5
	v_add_f32_e32 v3, v3, v9
	v_lshlrev_b32_e32 v11, 16, v5
	v_add_f32_e32 v4, v2, v3
	v_pk_mul_f32 v[2:3], v[10:11], v[10:11]
	s_lshl_b32 s0, s15, 2
	v_add_f32_e32 v3, v3, v4
	v_add_f32_e32 v2, v2, v3
	ds_bpermute_b32 v3, v199, v2
	v_mov_b32_e32 v34, s0
	s_waitcnt lgkmcnt(0)
	s_barrier
	v_add_f32_e32 v2, v2, v3
	v_fmamk_f32 v2, v2, 0x3c800000, v202
	v_rsq_f32_e32 v2, v2
	global_load_dword v170, v34, s[10:11]
	v_mul_f32_e32 v34, 0x3e38aa3b, v2
	v_mov_b64_e32 v[2:3], v[220:221]
	v_mov_b64_e32 v[4:5], v[222:223]
	v_mov_b64_e32 v[50:51], v[216:217]
	v_mov_b64_e32 v[52:53], v[218:219]
	v_mul_f32_e32 v9, v34, v48
	v_mul_f32_e32 v48, v34, v49
	v_mul_f32_e32 v46, v34, v46
	v_mul_f32_e32 v44, v34, v44
	v_mul_f32_e32 v38, v34, v38
	v_mul_f32_e32 v36, v34, v36
	v_mul_f32_e32 v8, v34, v8
	v_mul_f32_e32 v17, v34, v17
	v_mul_f32_e32 v16, v34, v16
	s_waitcnt vmcnt(0)
	v_mul_f32_e32 v9, v50, v9
	v_mul_f32_e32 v48, v51, v48
	v_cvt_pk_bf16_f32 v50, v9, v48
	v_mul_f32_e32 v9, v34, v54
	v_mul_f32_e32 v9, v52, v9
	v_mul_f32_e32 v48, v34, v55
	v_mul_f32_e32 v48, v53, v48
	v_cvt_pk_bf16_f32 v51, v9, v48
	v_mul_f32_e32 v9, v34, v56
	v_mul_f32_e32 v2, v2, v9
	v_mul_f32_e32 v9, v34, v57
	v_mul_f32_e32 v3, v3, v9
	v_cvt_pk_bf16_f32 v52, v2, v3
	v_mul_f32_e32 v2, v34, v58
	v_mul_f32_e32 v3, v34, v59
	v_mul_f32_e32 v2, v4, v2
	v_mul_f32_e32 v3, v5, v3
	v_cvt_pk_bf16_f32 v53, v2, v3
	v_mov_b64_e32 v[2:3], v[228:229]
	v_mov_b64_e32 v[4:5], v[230:231]
	v_mov_b64_e32 v[54:55], v[224:225]
	v_mov_b64_e32 v[56:57], v[226:227]
	v_mul_f32_e32 v9, v34, v47
	s_waitcnt vmcnt(0)
	v_mul_f32_e32 v9, v9, v54
	v_mul_f32_e32 v46, v46, v55
	v_cvt_pk_bf16_f32 v54, v9, v46
	v_mul_f32_e32 v9, v34, v45
	v_mul_f32_e32 v9, v9, v56
	v_mul_f32_e32 v44, v44, v57
	v_cvt_pk_bf16_f32 v55, v9, v44
	v_mul_f32_e32 v9, v34, v43
	v_mul_f32_e32 v2, v9, v2
	v_mul_f32_e32 v9, v34, v42
	v_mul_f32_e32 v3, v9, v3
	v_cvt_pk_bf16_f32 v56, v2, v3
	v_mul_f32_e32 v2, v34, v41
	v_mul_f32_e32 v3, v34, v40
	v_mul_f32_e32 v2, v2, v4
	v_mul_f32_e32 v3, v3, v5
	v_cvt_pk_bf16_f32 v57, v2, v3
	v_mov_b64_e32 v[2:3], v[236:237]
	v_mov_b64_e32 v[4:5], v[238:239]
	v_mov_b64_e32 v[40:41], v[232:233]
	v_mov_b64_e32 v[42:43], v[234:235]
	v_mul_f32_e32 v9, v34, v39
	s_waitcnt vmcnt(1)
	v_mul_f32_e32 v3, v8, v3
	s_waitcnt vmcnt(0)
	v_mul_f32_e32 v9, v9, v40
	v_mul_f32_e32 v38, v38, v41
	v_cvt_pk_bf16_f32 v58, v9, v38
	v_mul_f32_e32 v9, v34, v37
	v_mul_f32_e32 v9, v9, v42
	v_mul_f32_e32 v36, v36, v43
	v_cvt_pk_bf16_f32 v59, v9, v36
	v_mul_f32_e32 v9, v34, v35
	v_mul_f32_e32 v2, v9, v2
	v_cvt_pk_bf16_f32 v60, v2, v3
	v_mul_f32_e32 v2, v34, v7
	v_mul_f32_e32 v3, v34, v6
	v_mul_f32_e32 v2, v2, v4
	v_mul_f32_e32 v3, v3, v5
	v_cvt_pk_bf16_f32 v61, v2, v3
	v_mov_b64_e32 v[2:3], v[248:249]
	v_mov_b64_e32 v[4:5], v[250:251]
	v_mov_b64_e32 v[6:7], v[240:241]
	v_mov_b64_e32 v[8:9], v[242:243]
	s_waitcnt vmcnt(0)
	v_mul_f32_e32 v6, v17, v6
	v_mul_f32_e32 v7, v16, v7
	v_cvt_pk_bf16_f32 v82, v6, v7
	v_mul_f32_e32 v6, v34, v15
	v_mul_f32_e32 v6, v6, v8
	v_mul_f32_e32 v7, v34, v14
	v_mul_f32_e32 v7, v7, v9
	v_cvt_pk_bf16_f32 v83, v6, v7
	v_mul_f32_e32 v6, v34, v13
	v_mul_f32_e32 v2, v6, v2
	v_mul_f32_e32 v6, v34, v12
	v_mul_f32_e32 v3, v6, v3
	v_cvt_pk_bf16_f32 v84, v2, v3
	v_mul_f32_e32 v2, v34, v11
	v_mul_f32_e32 v3, v34, v10
	v_mul_f32_e32 v2, v2, v4
	v_mul_f32_e32 v3, v3, v5
	v_cvt_pk_bf16_f32 v85, v2, v3
	s_setprio 1
	v_or_b32_e32 v2, s17, v1
	v_mad_u32_u24 v189, v2, s6, v195
	ds_read_b128 v[2:5], v189
	v_or_b32_e32 v6, s18, v1
	v_mad_u32_u24 v62, v6, s6, v195
	s_add_i32 s19, s14, 2
	s_add_i32 s18, s14, 3
	s_or_b32 s0, s14, 4
	s_waitcnt lgkmcnt(0)
	v_mfma_f32_32x32x16_bf16 v[146:161], v[2:5], v[50:53], 0
	ds_read_b128 v[2:5], v189 offset:32
	s_waitcnt lgkmcnt(0)
	v_mfma_f32_32x32x16_bf16 v[146:161], v[2:5], v[54:57], v[146:161]
	ds_read_b128 v[2:5], v189 offset:64
	s_waitcnt lgkmcnt(0)
	v_mfma_f32_32x32x16_bf16 v[146:161], v[2:5], v[58:61], v[146:161]
	ds_read_b128 v[2:5], v189 offset:96
	s_waitcnt lgkmcnt(0)
	v_mfma_f32_32x32x16_bf16 v[146:161], v[2:5], v[82:85], v[146:161]
	ds_read_b128 v[2:5], v62
	s_waitcnt lgkmcnt(0)
	v_mfma_f32_32x32x16_bf16 v[66:81], v[2:5], v[50:53], 0
	ds_read_b128 v[2:5], v62 offset:32
	s_waitcnt lgkmcnt(0)
	v_mfma_f32_32x32x16_bf16 v[66:81], v[2:5], v[54:57], v[66:81]
	ds_read_b128 v[2:5], v62 offset:64
	s_waitcnt lgkmcnt(0)
	v_mfma_f32_32x32x16_bf16 v[66:81], v[2:5], v[58:61], v[66:81]
	ds_read_b128 v[2:5], v62 offset:96
	s_waitcnt lgkmcnt(0)
	v_mfma_f32_32x32x16_bf16 v[66:81], v[2:5], v[82:85], v[66:81]
	v_lshl_or_b32 v2, s19, 5, v1
	v_mad_u32_u24 v6, v2, s6, v195
	ds_read_b128 v[2:5], v6
	s_waitcnt lgkmcnt(0)
	v_mfma_f32_32x32x16_bf16 v[34:49], v[2:5], v[50:53], 0
	ds_read_b128 v[2:5], v6 offset:32
	s_waitcnt lgkmcnt(0)
	v_mfma_f32_32x32x16_bf16 v[34:49], v[2:5], v[54:57], v[34:49]
	ds_read_b128 v[2:5], v6 offset:64
	s_waitcnt lgkmcnt(0)
	v_mfma_f32_32x32x16_bf16 v[34:49], v[2:5], v[58:61], v[34:49]
	ds_read_b128 v[2:5], v6 offset:96
	s_waitcnt lgkmcnt(0)
	v_mfma_f32_32x32x16_bf16 v[34:49], v[2:5], v[82:85], v[34:49]
	v_lshl_or_b32 v2, s18, 5, v1
	v_mad_u32_u24 v63, v2, s6, v195
	ds_read_b128 v[2:5], v63
	ds_read_b128 v[86:89], v63 offset:32
	s_waitcnt lgkmcnt(1)
	v_mfma_f32_32x32x16_bf16 v[2:17], v[2:5], v[50:53], 0
	s_waitcnt lgkmcnt(0)
	v_mfma_f32_32x32x16_bf16 v[2:17], v[86:89], v[54:57], v[2:17]
	ds_read_b128 v[86:89], v63 offset:64
	s_waitcnt lgkmcnt(0)
	v_mfma_f32_32x32x16_bf16 v[2:17], v[86:89], v[58:61], v[2:17]
	ds_read_b128 v[86:89], v63 offset:96
	v_lshl_or_b32 v63, s0, 5, v1
	v_mad_u32_u24 v63, v63, s6, v195
	s_waitcnt lgkmcnt(0)
	v_mfma_f32_32x32x16_bf16 v[2:17], v[86:89], v[82:85], v[2:17]
	ds_read_b128 v[86:89], v63
	s_waitcnt lgkmcnt(0)
	v_mfma_f32_32x32x16_bf16 v[98:113], v[86:89], v[50:53], 0
	ds_read_b128 v[50:53], v63 offset:32
	s_waitcnt lgkmcnt(0)
	v_mfma_f32_32x32x16_bf16 v[98:113], v[50:53], v[54:57], v[98:113]
	ds_read_b128 v[50:53], v63 offset:64
	s_waitcnt lgkmcnt(0)
	v_mfma_f32_32x32x16_bf16 v[98:113], v[50:53], v[58:61], v[98:113]
	ds_read_b128 v[50:53], v63 offset:96
	s_waitcnt lgkmcnt(0)
	v_mfma_f32_32x32x16_bf16 v[98:113], v[50:53], v[82:85], v[98:113]
	s_setprio 0
	v_and_b32_e32 v86, 0xffff0000, v30
	v_lshlrev_b32_e32 v65, 16, v30
	v_lshlrev_b32_e32 v55, 16, v22
	v_and_b32_e32 v54, 0xffff0000, v22
	v_lshlrev_b32_e32 v53, 16, v23
	v_and_b32_e32 v52, 0xffff0000, v23
	v_lshlrev_b32_e32 v23, 16, v25
	v_and_b32_e32 v22, 0xffff0000, v25
	v_mul_f32_e32 v25, v86, v86
	v_lshlrev_b32_e32 v87, 16, v31
	v_fmac_f32_e32 v25, v65, v65
	v_and_b32_e32 v88, 0xffff0000, v31
	v_fmac_f32_e32 v25, v87, v87
	v_lshlrev_b32_e32 v89, 16, v32
	v_fmac_f32_e32 v25, v88, v88
	v_and_b32_e32 v90, 0xffff0000, v32
	v_fmac_f32_e32 v25, v89, v89
	v_lshlrev_b32_e32 v91, 16, v33
	v_fmac_f32_e32 v25, v90, v90
	v_and_b32_e32 v92, 0xffff0000, v33
	v_fmac_f32_e32 v25, v91, v91
	v_lshlrev_b32_e32 v64, 16, v26
	v_fmac_f32_e32 v25, v92, v92
	v_and_b32_e32 v63, 0xffff0000, v26
	v_fmac_f32_e32 v25, v64, v64
	v_lshlrev_b32_e32 v61, 16, v27
	v_fmac_f32_e32 v25, v63, v63
	v_and_b32_e32 v60, 0xffff0000, v27
	v_fmac_f32_e32 v25, v61, v61
	v_lshlrev_b32_e32 v59, 16, v28
	v_fmac_f32_e32 v25, v60, v60
	v_and_b32_e32 v58, 0xffff0000, v28
	v_fmac_f32_e32 v25, v59, v59
	v_lshlrev_b32_e32 v57, 16, v29
	v_fmac_f32_e32 v25, v58, v58
	v_and_b32_e32 v56, 0xffff0000, v29
	v_fmac_f32_e32 v25, v57, v57
	v_fmac_f32_e32 v25, v56, v56
	v_fmac_f32_e32 v25, v55, v55
	v_fmac_f32_e32 v25, v54, v54
	v_fmac_f32_e32 v25, v53, v53
	v_lshlrev_b32_e32 v51, 16, v24
	v_fmac_f32_e32 v25, v52, v52
	v_and_b32_e32 v24, 0xffff0000, v24
	v_fmac_f32_e32 v25, v51, v51
	v_fmac_f32_e32 v25, v24, v24
	v_fmac_f32_e32 v25, v23, v23
	v_lshlrev_b32_e32 v33, 16, v18
	v_fmac_f32_e32 v25, v22, v22
	v_and_b32_e32 v32, 0xffff0000, v18
	v_fmac_f32_e32 v25, v33, v33
	v_lshlrev_b32_e32 v31, 16, v19
	v_fmac_f32_e32 v25, v32, v32
	v_and_b32_e32 v30, 0xffff0000, v19
	v_fmac_f32_e32 v25, v31, v31
	v_and_b32_e32 v28, 0xffff0000, v20
	v_lshlrev_b32_e32 v29, 16, v20
	v_fmac_f32_e32 v25, v30, v30
	v_pk_mul_f32 v[18:19], v[28:29], v[28:29]
	v_and_b32_e32 v26, 0xffff0000, v21
	v_add_f32_e32 v19, v19, v25
	v_lshlrev_b32_e32 v27, 16, v21
	v_add_f32_e32 v20, v18, v19
	v_pk_mul_f32 v[18:19], v[26:27], v[26:27]
	s_nop 0
	v_add_f32_e32 v19, v19, v20
	v_add_f32_e32 v18, v18, v19
	ds_bpermute_b32 v19, v199, v18
	s_waitcnt lgkmcnt(0)
	v_add_f32_e32 v18, v18, v19
	v_fmamk_f32 v18, v18, 0x3c800000, v202
	v_rsq_f32_e32 v18, v18
	s_nop 0
	v_mul_f32_e32 v50, 0x3e38aa3b, v18
	v_mov_b64_e32 v[18:19], v[220:221]
	v_mov_b64_e32 v[20:21], v[222:223]
	v_mov_b64_e32 v[82:83], v[216:217]
	v_mov_b64_e32 v[84:85], v[218:219]
	v_mul_f32_e32 v25, v50, v65
	v_mul_f32_e32 v65, v50, v86
	v_mul_f32_e32 v63, v50, v63
	v_mul_f32_e32 v60, v50, v60
	v_mul_f32_e32 v54, v50, v54
	v_mul_f32_e32 v52, v50, v52
	v_mul_f32_e32 v24, v50, v24
	v_mul_f32_e32 v33, v50, v33
	v_mul_f32_e32 v32, v50, v32
	s_waitcnt vmcnt(0)
	v_mul_f32_e32 v25, v82, v25
	v_mul_f32_e32 v65, v83, v65
	v_cvt_pk_bf16_f32 v114, v25, v65
	v_mul_f32_e32 v25, v50, v87
	v_mul_f32_e32 v25, v84, v25
	v_mul_f32_e32 v65, v50, v88
	v_mul_f32_e32 v65, v85, v65
	v_cvt_pk_bf16_f32 v115, v25, v65
	v_mul_f32_e32 v25, v50, v89
	v_mul_f32_e32 v18, v18, v25
	v_mul_f32_e32 v25, v50, v90
	v_mul_f32_e32 v19, v19, v25
	v_cvt_pk_bf16_f32 v116, v18, v19
	v_mul_f32_e32 v18, v50, v91
	v_mul_f32_e32 v19, v50, v92
	v_mul_f32_e32 v18, v20, v18
	v_mul_f32_e32 v19, v21, v19
	v_cvt_pk_bf16_f32 v117, v18, v19
	v_mov_b64_e32 v[18:19], v[228:229]
	v_mov_b64_e32 v[20:21], v[230:231]
	v_mov_b64_e32 v[82:83], v[224:225]
	v_mov_b64_e32 v[84:85], v[226:227]
	v_mul_f32_e32 v25, v50, v64
	s_waitcnt vmcnt(0)
	v_mul_f32_e32 v25, v25, v82
	v_mul_f32_e32 v63, v63, v83
	v_cvt_pk_bf16_f32 v162, v25, v63
	v_mul_f32_e32 v25, v50, v61
	v_mul_f32_e32 v25, v25, v84
	v_mul_f32_e32 v60, v60, v85
	v_cvt_pk_bf16_f32 v163, v25, v60
	v_mul_f32_e32 v25, v50, v59
	v_mul_f32_e32 v18, v25, v18
	v_mul_f32_e32 v25, v50, v58
	v_mul_f32_e32 v19, v25, v19
	v_cvt_pk_bf16_f32 v164, v18, v19
	v_mul_f32_e32 v18, v50, v57
	v_mul_f32_e32 v19, v50, v56
	v_mul_f32_e32 v18, v18, v20
	v_mul_f32_e32 v19, v19, v21
	v_cvt_pk_bf16_f32 v165, v18, v19
	v_mov_b64_e32 v[18:19], v[236:237]
	v_mov_b64_e32 v[20:21], v[238:239]
	v_mov_b64_e32 v[56:57], v[232:233]
	v_mov_b64_e32 v[58:59], v[234:235]
	v_mul_f32_e32 v25, v50, v55
	s_waitcnt vmcnt(1)
	v_mul_f32_e32 v19, v24, v19
	s_waitcnt vmcnt(0)
	v_mul_f32_e32 v25, v25, v56
	v_mul_f32_e32 v54, v54, v57
	v_cvt_pk_bf16_f32 v166, v25, v54
	v_mul_f32_e32 v25, v50, v53
	v_mul_f32_e32 v25, v25, v58
	v_mul_f32_e32 v52, v52, v59
	v_cvt_pk_bf16_f32 v167, v25, v52
	v_mul_f32_e32 v25, v50, v51
	v_mul_f32_e32 v18, v25, v18
	v_cvt_pk_bf16_f32 v168, v18, v19
	v_mul_f32_e32 v18, v50, v23
	v_mul_f32_e32 v19, v50, v22
	v_mul_f32_e32 v18, v18, v20
	v_mul_f32_e32 v19, v19, v21
	v_cvt_pk_bf16_f32 v169, v18, v19
	v_mov_b64_e32 v[18:19], v[248:249]
	v_mov_b64_e32 v[20:21], v[250:251]
	v_mov_b64_e32 v[22:23], v[240:241]
	v_mov_b64_e32 v[24:25], v[242:243]
	s_waitcnt vmcnt(0)
	v_readlane_b32 s20, v247, 7
	v_readlane_b32 s21, v247, 33
	v_lshrrev_b32_e32 v82, 1, v194
	v_and_b32_e32 v83, 1, v194
	s_and_b32 s32, s20, 1
	s_lshl_b32 s21, s21, 1
	s_add_i32 s21, s21, s32
	s_lshl_b32 s21, s21, 5
	s_add_i32 s21, s21, -15
	v_add_u32_e32 v84, 32, v82
	v_min_u32_e32 v84, 46, v84
	v_add_u32_e32 v85, s21, v82
	v_add_u32_e32 v84, s21, v84
	s_lshr_b32 s21, s20, 1
	s_lshl_b32 s21, s21, 8
	v_max_i32_e32 v85, 0, v85
	v_max_i32_e32 v84, 0, v84
	v_mul_u32_u24_e32 v85, 0x1a00, v85
	v_mul_u32_u24_e32 v84, 0x1a00, v84
	v_lshl_add_u32 v85, v83, 7, v85
	v_lshl_add_u32 v84, v83, 7, v84
	v_add_u32_e32 v85, s21, v85
	v_add_u32_e32 v84, s21, v84
	s_lshl_b32 s32, s20, 9
	s_add_i32 m0, s32, 0x22000
	s_nop 0
	global_load_lds_dword v85, s[92:93]
	s_add_i32 m0, s32, 0x22100
	s_nop 0
	global_load_lds_dword v84, s[92:93]
	s_cmp_gt_u32 s20, 3
	s_cbranch_scc1 .Lp2pf_done
	v_readlane_b32 s21, v247, 33
	s_lshl_b32 s32, s20, 6
	v_lshl_add_u32 v84, v82, 1, s32
	s_and_b32 s32, s21, 1
	s_lshr_b32 s21, s21, 1
	v_add_u32_e32 v84, s32, v84
	s_lshl_b32 s21, s21, 16
	v_lshlrev_b32_e32 v84, 8, v84
	v_lshl_add_u32 v84, v83, 7, v84
	v_add_u32_e32 v84, s21, v84
	s_lshl_b32 s32, s20, 9
	s_add_i32 m0, s32, 0x23000
	s_nop 0
	global_load_lds_dword v84, s[84:85]
	s_add_i32 m0, s32, 0x23100
	s_nop 0
	global_load_lds_dword v84, s[86:87]
.Lp2pf_done:
	v_mul_f32_e32 v22, v33, v22
	v_mul_f32_e32 v23, v32, v23
	v_cvt_pk_bf16_f32 v208, v22, v23
	v_mul_f32_e32 v22, v50, v31
	v_mul_f32_e32 v22, v22, v24
	v_mul_f32_e32 v23, v50, v30
	v_mul_f32_e32 v23, v23, v25
	v_cvt_pk_bf16_f32 v209, v22, v23
	v_mul_f32_e32 v22, v50, v29
	v_mul_f32_e32 v18, v22, v18
	v_mul_f32_e32 v22, v50, v28
	v_mul_f32_e32 v19, v22, v19
	v_cvt_pk_bf16_f32 v210, v18, v19
	v_mul_f32_e32 v18, v50, v27
	v_mul_f32_e32 v19, v50, v26
	v_mul_f32_e32 v18, v18, v20
	v_mul_f32_e32 v19, v19, v21
	v_cvt_pk_bf16_f32 v211, v18, v19
	s_setprio 1
	ds_read_b128 v[18:21], v62
	ds_read_b128 v[22:25], v62 offset:32
	s_waitcnt lgkmcnt(1)
	v_mfma_f32_32x32x16_bf16 v[130:145], v[18:21], v[114:117], 0
	ds_read_b128 v[18:21], v62 offset:64
	s_waitcnt lgkmcnt(1)
	v_mfma_f32_32x32x16_bf16 v[130:145], v[22:25], v[162:165], v[130:145]
	s_waitcnt lgkmcnt(0)
	v_mfma_f32_32x32x16_bf16 v[130:145], v[18:21], v[166:169], v[130:145]
	ds_read_b128 v[18:21], v62 offset:96
	s_waitcnt lgkmcnt(0)
	v_mfma_f32_32x32x16_bf16 v[130:145], v[18:21], v[208:211], v[130:145]
	v_add_u32_e32 v18, s17, v196
	v_mad_u32_u24 v26, v18, s6, v195
	ds_read_b128 v[18:21], v26
	ds_read_b128 v[22:25], v26 offset:32
	s_waitcnt lgkmcnt(1)
	v_mfma_f32_32x32x16_bf16 v[82:97], v[18:21], v[114:117], 0
	ds_read_b128 v[18:21], v26 offset:64
	s_waitcnt lgkmcnt(1)
	v_mfma_f32_32x32x16_bf16 v[82:97], v[22:25], v[162:165], v[82:97]
	s_waitcnt lgkmcnt(0)
	v_mfma_f32_32x32x16_bf16 v[82:97], v[18:21], v[166:169], v[82:97]
	ds_read_b128 v[18:21], v26 offset:96
	s_waitcnt lgkmcnt(0)
	v_mfma_f32_32x32x16_bf16 v[82:97], v[18:21], v[208:211], v[82:97]
	v_add_u32_e32 v18, s17, v197
	v_mad_u32_u24 v26, v18, s6, v195
	ds_read_b128 v[18:21], v26
	ds_read_b128 v[22:25], v26 offset:32
	s_waitcnt lgkmcnt(1)
	v_mfma_f32_32x32x16_bf16 v[50:65], v[18:21], v[114:117], 0
	ds_read_b128 v[18:21], v26 offset:64
	s_waitcnt lgkmcnt(1)
	v_mfma_f32_32x32x16_bf16 v[50:65], v[22:25], v[162:165], v[50:65]
	s_waitcnt lgkmcnt(0)
	v_mfma_f32_32x32x16_bf16 v[50:65], v[18:21], v[166:169], v[50:65]
	ds_read_b128 v[18:21], v26 offset:96
	s_waitcnt lgkmcnt(0)
	v_mfma_f32_32x32x16_bf16 v[50:65], v[18:21], v[208:211], v[50:65]
	ds_read_b128 v[18:21], v189 offset:18432
	ds_read_b128 v[118:121], v189 offset:18464
	ds_read_b128 v[212:215], v189 offset:23072
	s_waitcnt lgkmcnt(2)
	v_mfma_f32_32x32x16_bf16 v[18:33], v[18:21], v[114:117], 0
	s_waitcnt lgkmcnt(1)
	v_mfma_f32_32x32x16_bf16 v[18:33], v[118:121], v[162:165], v[18:33]
	ds_read_b128 v[118:121], v189 offset:18496
	s_waitcnt lgkmcnt(0)
	v_mfma_f32_32x32x16_bf16 v[18:33], v[118:121], v[166:169], v[18:33]
	ds_read_b128 v[118:121], v189 offset:18528
	s_waitcnt lgkmcnt(0)
	v_mfma_f32_32x32x16_bf16 v[18:33], v[118:121], v[208:211], v[18:33]
	ds_read_b128 v[118:121], v189 offset:23040
	s_waitcnt lgkmcnt(0)
	v_mfma_f32_32x32x16_bf16 v[114:129], v[118:121], v[114:117], 0
	v_mfma_f32_32x32x16_bf16 v[114:129], v[212:215], v[162:165], v[114:129]
	ds_read_b128 v[162:165], v189 offset:23104
	s_waitcnt lgkmcnt(0)
	v_mfma_f32_32x32x16_bf16 v[114:129], v[162:165], v[166:169], v[114:129]
	ds_read_b128 v[162:165], v189 offset:23136
	s_waitcnt lgkmcnt(0)
	v_mfma_f32_32x32x16_bf16 v[114:129], v[162:165], v[208:211], v[114:129]
	s_setprio 0
	s_cmp_lg_u32 s16, 0
	v_mov_b32_e32 v162, 0xf149f2ca
	s_cselect_b64 s[4:5], -1, 0
	s_cmp_eq_u32 s16, 0
	v_mov_b32_e32 v215, 0xf149f2ca
	v_mov_b32_e32 v210, 0xf149f2ca
	v_mov_b32_e32 v211, 0xf149f2ca
	v_mov_b32_e32 v213, 0xf149f2ca
	v_mov_b32_e32 v214, 0xf149f2ca
	v_mov_b32_e32 v208, 0xf149f2ca
	v_mov_b32_e32 v209, 0xf149f2ca
	v_mov_b32_e32 v212, 0xf149f2ca
	v_mov_b32_e32 v191, 0xf149f2ca
	v_mov_b32_e32 v189, 0xf149f2ca
	v_mov_b32_e32 v169, 0xf149f2ca
	v_mov_b32_e32 v168, 0xf149f2ca
	v_mov_b32_e32 v167, 0xf149f2ca
	v_mov_b32_e32 v166, 0xf149f2ca
	v_mov_b32_e32 v165, 0xf149f2ca
	v_mov_b32_e32 v164, 0xf149f2ca
	v_mov_b32_e32 v163, 0xf149f2ca
	s_cbranch_scc1 .LBB0_284
	v_readlane_b32 s20, v247, 40
	v_readlane_b32 s21, v247, 41
	v_cndmask_b32_e64 v191, v153, v207, s[90:91]
	v_cndmask_b32_e64 v189, v154, v207, s[88:89]
	v_cndmask_b32_e64 v210, v146, v207, s[20:21]
	v_readlane_b32 s20, v247, 42
	v_readlane_b32 s21, v247, 43
	v_cndmask_b32_e64 v169, v155, v207, s[24:25]
	v_cndmask_b32_e64 v168, v156, v207, s[26:27]
	v_cndmask_b32_e64 v211, v147, v207, s[20:21]
	v_readlane_b32 s20, v247, 44
	v_readlane_b32 s21, v247, 45
	v_max3_f32 v146, v210, s23, v211
	v_cndmask_b32_e64 v167, v157, v207, s[28:29]
	v_cndmask_b32_e64 v213, v148, v207, s[20:21]
	v_readlane_b32 s20, v247, 46
	v_readlane_b32 s21, v247, 47
	v_cndmask_b32_e64 v166, v158, v207, s[30:31]
	v_cndmask_b32_e64 v165, v159, v207, s[34:35]
	v_cndmask_b32_e64 v214, v149, v207, s[20:21]
	v_readlane_b32 s20, v247, 48
	v_readlane_b32 s21, v247, 49
	v_max3_f32 v146, v146, v213, v214
	v_cndmask_b32_e64 v164, v160, v207, s[36:37]
	v_cndmask_b32_e64 v208, v150, v207, s[20:21]
	v_readlane_b32 s20, v247, 50
	v_readlane_b32 s21, v247, 51
	v_cndmask_b32_e64 v163, v161, v207, s[38:39]
	s_nop 0
	v_cndmask_b32_e64 v209, v151, v207, s[20:21]
	v_readlane_b32 s20, v247, 52
	v_readlane_b32 s21, v247, 53
	v_max3_f32 v146, v146, v208, v209
	s_nop 0
	v_cndmask_b32_e64 v212, v152, v207, s[20:21]
	v_max3_f32 v146, v146, v212, v191
	v_max3_f32 v146, v146, v189, v169
	v_max3_f32 v146, v146, v168, v167
	v_max3_f32 v146, v146, v166, v165
	v_max3_f32 v215, v146, v164, v163
